# tile-boundary wave-group re-sync also in FGEMM (Fourier) and MoE down-projection GEMMs
# baseline (speedup 1.0000x reference)
; #define PG8_STAGE(bufoff, gbase, voff) do { _Pragma("unroll") for (int _i = 0; _i < 2; ++_i) \
;         __builtin_amdgcn_global_load_lds((const unsigned*)((const char*)(gbase) + (voff)[_i]), (LAS unsigned*)(lds + (bufoff) + ldsw + _i * 8192), 16, 0, 0); } while (0)
; #define PG8_STAGE_A(bufoff, gbase, h, vv) do { if constexpr (GATHER) { _Pragma("unroll") for (int _i = 0; _i < 2; ++_i) \
;         __builtin_amdgcn_global_load_lds((const unsigned*)((const char*)(gbase) + (vv)[h][_i]), (LAS unsigned*)(lds + (bufoff) + ldsw + _i * 8192), 16, 0, 0); } \
;         else { PG8_STAGE(bufoff, (gbase) + (h) * hstepA, voffA); } } while (0)
; #define PG8_LDA(dst, b, h) do { _Pragma("unroll") for (int m = 0; m < 4; ++m) _Pragma("unroll") for (int k = 0; k < 2; ++k) dst[m][k] = *(const LAS bf16x8*)(lds + PG8_SA(b, h) + aoff + m * 2048 + k * 1024); } while (0)
; #define PG8_LDB(dst, b, h) do { _Pragma("unroll") for (int n = 0; n < 2; ++n) _Pragma("unroll") for (int k = 0; k < 2; ++k) dst[n][k] = *(const LAS bf16x8*)(lds + PG8_SB(b, h) + boff + n * 2048 + k * 1024); } while (0)
; #define PG8_WAIT_L(n) asm volatile("s_waitcnt lgkmcnt(" #n ")" ::: "memory")
; template <class Epi, class Sched>
; __device__ __forceinline__ void gemm_phase(LAS unsigned char* lds, const int K, const int lda, const int ldb, const Sched& S, const Epi& E) {
;     ...
;         for (int t = 0; t < nt; t += 2) {
;             const bool last = (t == nt - 2);
;             const char* a1 = cA + (size_t)(t + 1) * kstep;
;             const char* a2 = last ? nA : cA + (size_t)(t + 2) * kstep; const char* b2 = last ? nB : cB + (size_t)(t + 2) * kstep;
;             const char* a3 = a2 + kstep; const char* b3 = b2 + kstep;
;             PG8_LDB(B0, 0, 0); PG8_SCHED; PG8_LDA(At, 0, 0); PG8_STAGE_A(PG8_SA(1, 1), a1, 1, vcur);
;             if constexpr (GATHER) { if (last) {
; #pragma unroll
;                 for (int h = 0; h < 2; ++h)
; #pragma unroll
;                     for (int i = 0; i < 2; ++i) vcur[h][i] = vnxt[h][i]; } }
;             PG8_WAIT_L(8); PG8_BAR; PG8_WAIT_L(0); PG8_MMA(0, 0, At, B0); PG8_BAR; PG8_SCHED;
;             PG8_LDB(B1, 0, 1); PG8_STAGE(PG8_SB(0, 0), b2, voffB);
;             PG8_BAR; PG8_WAIT_L(0); PG8_MMA(0, 1, At, B1); PG8_BAR;
;             PG8_LDA(At, 0, 1); PG8_STAGE_A(PG8_SA(0, 0), a2, 0, vcur);
;             PG8_BAR; PG8_WAIT_L(0); PG8_MMA(1, 0, At, B0); PG8_BAR; PG8_SCHED;
.LBB0_392:
	s_add_u32 s2, s0, s12
	s_addc_u32 s3, s1, s13
	s_add_u32 s2, s2, 0x100
	s_addc_u32 s3, s3, 0
	s_add_u32 s14, s78, s12
	s_addc_u32 s15, s79, s13
	s_add_i32 s20, 0, 0x10000
	v_add_u32_e32 v160, s20, v145
	ds_read_b128 v[148:151], v160
	ds_read_b128 v[152:155], v160 offset:1024
	ds_read_b128 v[156:159], v160 offset:2048
	ds_read_b128 v[160:163], v160 offset:3072
	s_cmpk_eq_i32 s12, 0x1b00
	s_cselect_b32 s17, s11, s3
	s_cselect_b32 s16, s10, s2
	s_cselect_b32 s15, s5, s15
	s_cselect_b32 s14, s4, s14
	v_lshl_add_u64 v[214:215], v[140:141], 0, s[12:13]
	s_add_i32 m0, s54, 0xc000
	ds_read_b128 v[164:167], v147
	ds_read_b128 v[168:171], v147 offset:1024
	ds_read_b128 v[172:175], v147 offset:2048
	ds_read_b128 v[176:179], v147 offset:3072
	ds_read_b128 v[180:183], v147 offset:4096
	ds_read_b128 v[184:187], v147 offset:5120
	ds_read_b128 v[188:191], v147 offset:6144
	ds_read_b128 v[192:195], v147 offset:7168
	global_load_lds_dwordx4 v[214:215], off
	v_lshl_add_u64 v[214:215], v[142:143], 0, s[12:13]
	s_add_i32 m0, s54, 0xe000
	s_nop 0
	global_load_lds_dwordx4 v[214:215], off
	s_waitcnt lgkmcnt(8)
	s_barrier
	s_waitcnt lgkmcnt(0)
	s_setprio 1
	s_waitcnt lgkmcnt(0)
	v_mfma_f32_16x16x32_bf16 v[126:129], v[148:151], v[164:167], v[126:129]
	v_mfma_f32_16x16x32_bf16 v[122:125], v[156:159], v[164:167], v[122:125]
	v_mfma_f32_16x16x32_bf16 v[118:121], v[148:151], v[172:175], v[118:121]
	v_mfma_f32_16x16x32_bf16 v[114:117], v[156:159], v[172:175], v[114:117]
	v_mfma_f32_16x16x32_bf16 v[110:113], v[148:151], v[180:183], v[110:113]
	v_mfma_f32_16x16x32_bf16 v[106:109], v[156:159], v[180:183], v[106:109]
	v_mfma_f32_16x16x32_bf16 v[102:105], v[148:151], v[188:191], v[102:105]
	v_mfma_f32_16x16x32_bf16 v[98:101], v[156:159], v[188:191], v[98:101]
	v_mfma_f32_16x16x32_bf16 v[126:129], v[152:155], v[168:171], v[126:129]
	v_mfma_f32_16x16x32_bf16 v[122:125], v[160:163], v[168:171], v[122:125]
	v_mfma_f32_16x16x32_bf16 v[118:121], v[152:155], v[176:179], v[118:121]
	v_mfma_f32_16x16x32_bf16 v[114:117], v[160:163], v[176:179], v[114:117]
	v_mfma_f32_16x16x32_bf16 v[110:113], v[152:155], v[184:187], v[110:113]
	v_mfma_f32_16x16x32_bf16 v[106:109], v[160:163], v[184:187], v[106:109]
	v_mfma_f32_16x16x32_bf16 v[102:105], v[152:155], v[192:195], v[102:105]
	v_mfma_f32_16x16x32_bf16 v[98:101], v[160:163], v[192:195], v[98:101]
	s_setprio 0
	s_barrier
	s_add_i32 s21, 0, 0x14000
	v_add_u32_e32 v214, s21, v145
	s_add_i32 s2, s20, s63
	ds_read_b128 v[216:219], v214
	ds_read_b128 v[220:223], v214 offset:1024
	ds_read_b128 v[224:227], v214 offset:2048
	ds_read_b128 v[228:231], v214 offset:3072
	v_lshl_add_u64 v[214:215], s[14:15], 0, v[0:1]
	s_mov_b32 m0, s2
	v_lshl_add_u64 v[232:233], s[14:15], 0, v[134:135]
	global_load_lds_dwordx4 v[214:215], off
	s_add_i32 m0, s2, 0x2000
	s_nop 0
	global_load_lds_dwordx4 v[232:233], off
	s_barrier
	s_waitcnt lgkmcnt(0)
	s_setprio 1
	s_waitcnt lgkmcnt(0)
	v_mfma_f32_16x16x32_bf16 v[94:97], v[216:219], v[164:167], v[94:97]
	v_mfma_f32_16x16x32_bf16 v[90:93], v[224:227], v[164:167], v[90:93]
	v_mfma_f32_16x16x32_bf16 v[86:89], v[216:219], v[172:175], v[86:89]
	v_mfma_f32_16x16x32_bf16 v[82:85], v[224:227], v[172:175], v[82:85]
	v_mfma_f32_16x16x32_bf16 v[78:81], v[216:219], v[180:183], v[78:81]
	v_mfma_f32_16x16x32_bf16 v[74:77], v[224:227], v[180:183], v[74:77]
	v_mfma_f32_16x16x32_bf16 v[70:73], v[216:219], v[188:191], v[70:73]
	v_mfma_f32_16x16x32_bf16 v[66:69], v[224:227], v[188:191], v[66:69]
	v_mfma_f32_16x16x32_bf16 v[94:97], v[220:223], v[168:171], v[94:97]
	v_mfma_f32_16x16x32_bf16 v[90:93], v[228:231], v[168:171], v[90:93]
	v_mfma_f32_16x16x32_bf16 v[86:89], v[220:223], v[176:179], v[86:89]
	v_mfma_f32_16x16x32_bf16 v[82:85], v[228:231], v[176:179], v[82:85]
	v_mfma_f32_16x16x32_bf16 v[78:81], v[220:223], v[184:187], v[78:81]
	v_mfma_f32_16x16x32_bf16 v[74:77], v[228:231], v[184:187], v[74:77]
	v_mfma_f32_16x16x32_bf16 v[70:73], v[220:223], v[192:195], v[70:73]
	v_mfma_f32_16x16x32_bf16 v[66:69], v[228:231], v[192:195], v[66:69]
	s_setprio 0
	s_mov_b32 m0, s54
	v_lshl_add_u64 v[234:235], s[16:17], 0, v[130:131]
	s_barrier
	ds_read_b128 v[164:167], v147 offset:16384
	ds_read_b128 v[168:171], v147 offset:17408
	ds_read_b128 v[172:175], v147 offset:18432
	ds_read_b128 v[176:179], v147 offset:19456
	ds_read_b128 v[180:183], v147 offset:20480
	ds_read_b128 v[184:187], v147 offset:21504
	ds_read_b128 v[188:191], v147 offset:22528
	ds_read_b128 v[192:195], v147 offset:23552
	global_load_lds_dwordx4 v[234:235], off
	v_lshl_add_u64 v[236:237], s[16:17], 0, v[132:133]
	s_mov_b32 m0, s55
	s_nop 0
	global_load_lds_dwordx4 v[236:237], off
	s_barrier
	s_waitcnt lgkmcnt(0)
	s_setprio 1
	s_waitcnt lgkmcnt(0)
	v_mfma_f32_16x16x32_bf16 v[62:65], v[148:151], v[164:167], v[62:65]
	v_mfma_f32_16x16x32_bf16 v[58:61], v[156:159], v[164:167], v[58:61]
	v_mfma_f32_16x16x32_bf16 v[54:57], v[148:151], v[172:175], v[54:57]
	v_mfma_f32_16x16x32_bf16 v[50:53], v[156:159], v[172:175], v[50:53]
	v_mfma_f32_16x16x32_bf16 v[46:49], v[148:151], v[180:183], v[46:49]
	v_mfma_f32_16x16x32_bf16 v[42:45], v[156:159], v[180:183], v[42:45]
	v_mfma_f32_16x16x32_bf16 v[38:41], v[148:151], v[188:191], v[38:41]
	v_mfma_f32_16x16x32_bf16 v[34:37], v[156:159], v[188:191], v[34:37]
	v_mfma_f32_16x16x32_bf16 v[62:65], v[152:155], v[168:171], v[62:65]
	v_mfma_f32_16x16x32_bf16 v[58:61], v[160:163], v[168:171], v[58:61]
	v_mfma_f32_16x16x32_bf16 v[54:57], v[152:155], v[176:179], v[54:57]
	v_mfma_f32_16x16x32_bf16 v[50:53], v[160:163], v[176:179], v[50:53]
	v_mfma_f32_16x16x32_bf16 v[46:49], v[152:155], v[184:187], v[46:49]
	v_mfma_f32_16x16x32_bf16 v[42:45], v[160:163], v[184:187], v[42:45]
	v_mfma_f32_16x16x32_bf16 v[38:41], v[152:155], v[192:195], v[38:41]
	v_mfma_f32_16x16x32_bf16 v[34:37], v[160:163], v[192:195], v[34:37]
	s_setprio 0
	s_barrier
; #define PG8_STAGE(bufoff, gbase, voff) do { _Pragma("unroll") for (int _i = 0; _i < 2; ++_i) \
;         __builtin_amdgcn_global_load_lds((const unsigned*)((const char*)(gbase) + (voff)[_i]), (LAS unsigned*)(lds + (bufoff) + ldsw + _i * 8192), 16, 0, 0); } while (0)
; #define PG8_STAGE_A(bufoff, gbase, h, vv) do { if constexpr (GATHER) { _Pragma("unroll") for (int _i = 0; _i < 2; ++_i) \
;         __builtin_amdgcn_global_load_lds((const unsigned*)((const char*)(gbase) + (vv)[h][_i]), (LAS unsigned*)(lds + (bufoff) + ldsw + _i * 8192), 16, 0, 0); } \
;         else { PG8_STAGE(bufoff, (gbase) + (h) * hstepA, voffA); } } while (0)
; #define PG8_LDA(dst, b, h) do { _Pragma("unroll") for (int m = 0; m < 4; ++m) _Pragma("unroll") for (int k = 0; k < 2; ++k) dst[m][k] = *(const LAS bf16x8*)(lds + PG8_SA(b, h) + aoff + m * 2048 + k * 1024); } while (0)
; #define PG8_LDB(dst, b, h) do { _Pragma("unroll") for (int n = 0; n < 2; ++n) _Pragma("unroll") for (int k = 0; k < 2; ++k) dst[n][k] = *(const LAS bf16x8*)(lds + PG8_SB(b, h) + boff + n * 2048 + k * 1024); } while (0)
; #define PG8_MMA(ai, bj, At, Bt) do { __builtin_amdgcn_s_setprio(1); _Pragma("unroll") for (int m = 0; m < 4; ++m) _Pragma("unroll") for (int n = 0; n < 2; ++n) _Pragma("unroll") for (int k = 0; k < 2; ++k) \
;         acc[ai][bj][m][n] = __builtin_amdgcn_mfma_f32_16x16x32_bf16(Bt[n][k], At[m][k], acc[ai][bj][m][n], 0, 0, 0); __builtin_amdgcn_s_setprio(0); } while (0)
; #define PG8_WAIT_V(n) asm volatile("s_waitcnt vmcnt(" #n ")" ::: "memory")
; #define PG8_WAIT_L(n) asm volatile("s_waitcnt lgkmcnt(" #n ")" ::: "memory")
; #define PG8_BAR __builtin_amdgcn_s_barrier()
; template <class Epi, class Sched>
; __device__ __forceinline__ void gemm_phase(LAS unsigned char* lds, const int K, const int lda, const int ldb, const Sched& S, const Epi& E) {
;     ...
;             PG8_STAGE(PG8_SB(0, 1), b2 + hstepB, voffB);
;             PG8_WAIT_V(6); PG8_BAR; PG8_MMA(1, 1, At, B1); PG8_BAR;
;             PG8_LDB(B0, 1, 0); PG8_SCHED; PG8_LDA(At, 1, 0); PG8_STAGE_A(PG8_SA(0, 1), a2, 1, vcur);
;             PG8_WAIT_L(8); PG8_BAR; PG8_WAIT_L(0); PG8_MMA(0, 0, At, B0); PG8_BAR; PG8_SCHED;
;             PG8_LDB(B1, 1, 1); PG8_STAGE(PG8_SB(1, 0), b3, voffB);
;             PG8_BAR; PG8_WAIT_L(0); PG8_MMA(0, 1, At, B1); PG8_BAR;
;             PG8_LDA(At, 1, 1); PG8_STAGE_A(PG8_SA(1, 0), a3, 0, vcur);
	s_add_u32 s2, s14, 0xe0000
	s_addc_u32 s3, s15, 0
	s_add_i32 s20, s21, s63
	v_lshl_add_u64 v[148:149], s[2:3], 0, v[0:1]
	s_mov_b32 m0, s20
	s_nop 0
	global_load_lds_dwordx4 v[148:149], off
	v_lshl_add_u64 v[148:149], s[2:3], 0, v[134:135]
	s_add_i32 m0, s20, 0x2000
	s_nop 0
	global_load_lds_dwordx4 v[148:149], off
	s_waitcnt vmcnt(6)
	s_barrier
	s_setprio 1
	v_mfma_f32_16x16x32_bf16 v[30:33], v[216:219], v[164:167], v[30:33]
	v_mfma_f32_16x16x32_bf16 v[26:29], v[224:227], v[164:167], v[26:29]
	v_mfma_f32_16x16x32_bf16 v[22:25], v[216:219], v[172:175], v[22:25]
	v_mfma_f32_16x16x32_bf16 v[18:21], v[224:227], v[172:175], v[18:21]
	v_mfma_f32_16x16x32_bf16 v[14:17], v[216:219], v[180:183], v[14:17]
	v_mfma_f32_16x16x32_bf16 v[10:13], v[224:227], v[180:183], v[10:13]
	v_mfma_f32_16x16x32_bf16 v[6:9], v[216:219], v[188:191], v[6:9]
	v_mfma_f32_16x16x32_bf16 v[2:5], v[224:227], v[188:191], v[2:5]
	v_mfma_f32_16x16x32_bf16 v[30:33], v[220:223], v[168:171], v[30:33]
	v_mfma_f32_16x16x32_bf16 v[26:29], v[228:231], v[168:171], v[26:29]
	v_mfma_f32_16x16x32_bf16 v[22:25], v[220:223], v[176:179], v[22:25]
	v_mfma_f32_16x16x32_bf16 v[18:21], v[228:231], v[176:179], v[18:21]
	v_mfma_f32_16x16x32_bf16 v[14:17], v[220:223], v[184:187], v[14:17]
	v_mfma_f32_16x16x32_bf16 v[10:13], v[228:231], v[184:187], v[10:13]
	v_mfma_f32_16x16x32_bf16 v[6:9], v[220:223], v[192:195], v[6:9]
	v_mfma_f32_16x16x32_bf16 v[2:5], v[228:231], v[192:195], v[2:5]
	s_setprio 0
	s_add_i32 s20, 0, 0x18000
	v_add_u32_e32 v160, s20, v145
	s_barrier
	ds_read_b128 v[148:151], v160
	ds_read_b128 v[152:155], v160 offset:1024
	ds_read_b128 v[156:159], v160 offset:2048
	ds_read_b128 v[160:163], v160 offset:3072
	s_add_u32 s2, s16, 0xe0000
	s_addc_u32 s3, s17, 0
	s_mov_b32 m0, s69
	v_lshl_add_u64 v[216:217], s[2:3], 0, v[130:131]
	ds_read_b128 v[164:167], v147 offset:32768
	ds_read_b128 v[168:171], v147 offset:33792
	ds_read_b128 v[172:175], v147 offset:34816
	ds_read_b128 v[176:179], v147 offset:35840
	ds_read_b128 v[180:183], v147 offset:36864
	ds_read_b128 v[184:187], v147 offset:37888
	ds_read_b128 v[188:191], v147 offset:38912
	ds_read_b128 v[192:195], v147 offset:39936
	global_load_lds_dwordx4 v[216:217], off
	v_lshl_add_u64 v[216:217], s[2:3], 0, v[132:133]
	s_mov_b32 m0, s70
	s_nop 0
	global_load_lds_dwordx4 v[216:217], off
	s_waitcnt lgkmcnt(8)
	s_barrier
	s_waitcnt lgkmcnt(0)
	s_setprio 1
	s_waitcnt lgkmcnt(0)
	v_mfma_f32_16x16x32_bf16 v[126:129], v[148:151], v[164:167], v[126:129]
	v_mfma_f32_16x16x32_bf16 v[122:125], v[156:159], v[164:167], v[122:125]
	v_mfma_f32_16x16x32_bf16 v[118:121], v[148:151], v[172:175], v[118:121]
	v_mfma_f32_16x16x32_bf16 v[114:117], v[156:159], v[172:175], v[114:117]
	v_mfma_f32_16x16x32_bf16 v[110:113], v[148:151], v[180:183], v[110:113]
	v_mfma_f32_16x16x32_bf16 v[106:109], v[156:159], v[180:183], v[106:109]
	v_mfma_f32_16x16x32_bf16 v[102:105], v[148:151], v[188:191], v[102:105]
	v_mfma_f32_16x16x32_bf16 v[98:101], v[156:159], v[188:191], v[98:101]
	v_mfma_f32_16x16x32_bf16 v[126:129], v[152:155], v[168:171], v[126:129]
	v_mfma_f32_16x16x32_bf16 v[122:125], v[160:163], v[168:171], v[122:125]
	v_mfma_f32_16x16x32_bf16 v[118:121], v[152:155], v[176:179], v[118:121]
	v_mfma_f32_16x16x32_bf16 v[114:117], v[160:163], v[176:179], v[114:117]
	v_mfma_f32_16x16x32_bf16 v[110:113], v[152:155], v[184:187], v[110:113]
	v_mfma_f32_16x16x32_bf16 v[106:109], v[160:163], v[184:187], v[106:109]
	v_mfma_f32_16x16x32_bf16 v[102:105], v[152:155], v[192:195], v[102:105]
	v_mfma_f32_16x16x32_bf16 v[98:101], v[160:163], v[192:195], v[98:101]
	s_setprio 0
	s_barrier
	s_add_i32 s16, 0, 0x1c000
	s_add_i32 s2, s20, s63
	v_add_u32_e32 v228, s16, v145
	v_lshl_add_u64 v[214:215], v[214:215], 0, s[64:65]
	s_mov_b32 m0, s2
	ds_read_b128 v[216:219], v228
	ds_read_b128 v[220:223], v228 offset:1024
	ds_read_b128 v[224:227], v228 offset:2048
	ds_read_b128 v[228:231], v228 offset:3072
	global_load_lds_dwordx4 v[214:215], off
	v_lshl_add_u64 v[214:215], v[232:233], 0, s[64:65]
	s_add_i32 m0, s2, 0x2000
	s_nop 0
	global_load_lds_dwordx4 v[214:215], off
	s_barrier
	s_waitcnt lgkmcnt(0)
	s_setprio 1
	s_waitcnt lgkmcnt(0)
	v_mfma_f32_16x16x32_bf16 v[94:97], v[216:219], v[164:167], v[94:97]
	v_mfma_f32_16x16x32_bf16 v[90:93], v[224:227], v[164:167], v[90:93]
	v_mfma_f32_16x16x32_bf16 v[86:89], v[216:219], v[172:175], v[86:89]
	v_mfma_f32_16x16x32_bf16 v[82:85], v[224:227], v[172:175], v[82:85]
	v_mfma_f32_16x16x32_bf16 v[78:81], v[216:219], v[180:183], v[78:81]
	v_mfma_f32_16x16x32_bf16 v[74:77], v[224:227], v[180:183], v[74:77]
	v_mfma_f32_16x16x32_bf16 v[70:73], v[216:219], v[188:191], v[70:73]
	v_mfma_f32_16x16x32_bf16 v[66:69], v[224:227], v[188:191], v[66:69]
	v_mfma_f32_16x16x32_bf16 v[94:97], v[220:223], v[168:171], v[94:97]
	v_mfma_f32_16x16x32_bf16 v[90:93], v[228:231], v[168:171], v[90:93]
	v_mfma_f32_16x16x32_bf16 v[86:89], v[220:223], v[176:179], v[86:89]
	v_mfma_f32_16x16x32_bf16 v[82:85], v[228:231], v[176:179], v[82:85]
	v_mfma_f32_16x16x32_bf16 v[78:81], v[220:223], v[184:187], v[78:81]
	v_mfma_f32_16x16x32_bf16 v[74:77], v[228:231], v[184:187], v[74:77]
	v_mfma_f32_16x16x32_bf16 v[70:73], v[220:223], v[192:195], v[70:73]
	v_mfma_f32_16x16x32_bf16 v[66:69], v[228:231], v[192:195], v[66:69]
	s_setprio 0
	s_mov_b32 m0, s71
	v_lshl_add_u64 v[214:215], v[234:235], 0, s[64:65]
	s_barrier
	ds_read_b128 v[164:167], v147 offset:49152
	ds_read_b128 v[168:171], v147 offset:50176
	ds_read_b128 v[172:175], v147 offset:51200
	ds_read_b128 v[176:179], v147 offset:52224
	ds_read_b128 v[180:183], v147 offset:53248
	ds_read_b128 v[184:187], v147 offset:54272
	ds_read_b128 v[188:191], v147 offset:55296
	ds_read_b128 v[192:195], v147 offset:56320
	global_load_lds_dwordx4 v[214:215], off
	v_lshl_add_u64 v[214:215], v[236:237], 0, s[64:65]
	s_mov_b32 m0, s72
	s_nop 0
	global_load_lds_dwordx4 v[214:215], off
	s_barrier
; __device__ __forceinline__ unsigned pk2(float lo, float hi) { unsigned r; asm("v_cvt_pk_bf16_f32 %0, %1, %2" : "=v"(r) : "v"(lo), "v"(hi)); return r; }
; #define PG8_STAGE(bufoff, gbase, voff) do { _Pragma("unroll") for (int _i = 0; _i < 2; ++_i) \
;         __builtin_amdgcn_global_load_lds((const unsigned*)((const char*)(gbase) + (voff)[_i]), (LAS unsigned*)(lds + (bufoff) + ldsw + _i * 8192), 16, 0, 0); } while (0)
; #define PG8_MMA(ai, bj, At, Bt) do { __builtin_amdgcn_s_setprio(1); _Pragma("unroll") for (int m = 0; m < 4; ++m) _Pragma("unroll") for (int n = 0; n < 2; ++n) _Pragma("unroll") for (int k = 0; k < 2; ++k) \
;         acc[ai][bj][m][n] = __builtin_amdgcn_mfma_f32_16x16x32_bf16(Bt[n][k], At[m][k], acc[ai][bj][m][n], 0, 0, 0); __builtin_amdgcn_s_setprio(0); } while (0)
; #define PG8_WAIT_V(n) asm volatile("s_waitcnt vmcnt(" #n ")" ::: "memory")
; #define PG8_WAIT_L(n) asm volatile("s_waitcnt lgkmcnt(" #n ")" ::: "memory")
; #define PG8_BAR __builtin_amdgcn_s_barrier()
; #define PG8_SCHED __builtin_amdgcn_sched_barrier(0)
; template <class Epi, class Sched>
; __device__ __forceinline__ void gemm_phase(LAS unsigned char* lds, const int K, const int lda, const int ldb, const Sched& S, const Epi& E) {
;     ...
;             PG8_BAR; PG8_WAIT_L(0); PG8_MMA(1, 0, At, B0); PG8_BAR; PG8_SCHED;
;             PG8_STAGE(PG8_SB(1, 1), b3 + hstepB, voffB);
;             PG8_WAIT_V(6); PG8_BAR; PG8_MMA(1, 1, At, B1); PG8_BAR;
;         }
;         if constexpr (GATHER) { Unit n2; if (has_next && S.next(ui + 2, n2)) ld_ix(n2.pm, ix1); }
;         if constexpr (!Epi::AFTER_DRAIN) E(acc, cur, wr, wc, fr, fq);
;         if (!has_next) break;
;     __device__ __forceinline__ void operator()(const Acc& acc, const Unit& u, int wr, int wc, int fr, int fq) const {
;         const int row0 = u.pm * BM + wr * 64 + fr, col0 = u.pn * BM + wc * 32 + 8 * fq;
; #pragma unroll
;         for (int ai = 0; ai < 2; ++ai)
; #pragma unroll
;             for (int m = 0; m < 4; ++m) { bf16_t* rp = O + (size_t)(row0 + ai * HALF + m * 16) * ld + col0;
; #pragma unroll
;                 for (int bj = 0; bj < 2; ++bj) { const f32x4 v0 = acc[ai][bj][m][0], v1 = acc[ai][bj][m][1];
;                     u32x4 o; o.x = pk2(v0[0], v0[1]); o.y = pk2(v0[2], v0[3]); o.z = pk2(v1[0], v1[1]); o.w = pk2(v1[2], v1[3]);
;                     *(u32x4*)(rp + bj * HALF) = o; } }
	s_waitcnt lgkmcnt(0)
	s_setprio 1
	s_waitcnt lgkmcnt(0)
	v_mfma_f32_16x16x32_bf16 v[62:65], v[148:151], v[164:167], v[62:65]
	v_mfma_f32_16x16x32_bf16 v[58:61], v[156:159], v[164:167], v[58:61]
	v_mfma_f32_16x16x32_bf16 v[54:57], v[148:151], v[172:175], v[54:57]
	v_mfma_f32_16x16x32_bf16 v[50:53], v[156:159], v[172:175], v[50:53]
	v_mfma_f32_16x16x32_bf16 v[46:49], v[148:151], v[180:183], v[46:49]
	v_mfma_f32_16x16x32_bf16 v[42:45], v[156:159], v[180:183], v[42:45]
	v_mfma_f32_16x16x32_bf16 v[38:41], v[148:151], v[188:191], v[38:41]
	v_mfma_f32_16x16x32_bf16 v[34:37], v[156:159], v[188:191], v[34:37]
	v_mfma_f32_16x16x32_bf16 v[62:65], v[152:155], v[168:171], v[62:65]
	v_mfma_f32_16x16x32_bf16 v[58:61], v[160:163], v[168:171], v[58:61]
	v_mfma_f32_16x16x32_bf16 v[54:57], v[152:155], v[176:179], v[54:57]
	v_mfma_f32_16x16x32_bf16 v[50:53], v[160:163], v[176:179], v[50:53]
	v_mfma_f32_16x16x32_bf16 v[46:49], v[152:155], v[184:187], v[46:49]
	v_mfma_f32_16x16x32_bf16 v[42:45], v[160:163], v[184:187], v[42:45]
	v_mfma_f32_16x16x32_bf16 v[38:41], v[152:155], v[192:195], v[38:41]
	v_mfma_f32_16x16x32_bf16 v[34:37], v[160:163], v[192:195], v[34:37]
	s_setprio 0
	s_barrier
	s_add_u32 s2, s14, 0xe0080
	s_addc_u32 s3, s15, 0
	s_add_i32 s14, s16, s63
	v_lshl_add_u64 v[148:149], s[2:3], 0, v[0:1]
	s_mov_b32 m0, s14
	s_nop 0
	global_load_lds_dwordx4 v[148:149], off
	v_lshl_add_u64 v[148:149], s[2:3], 0, v[134:135]
	s_add_i32 m0, s14, 0x2000
	s_nop 0
	global_load_lds_dwordx4 v[148:149], off
	s_waitcnt vmcnt(6)
	s_barrier
	s_setprio 1
	v_mfma_f32_16x16x32_bf16 v[30:33], v[216:219], v[164:167], v[30:33]
	v_mfma_f32_16x16x32_bf16 v[26:29], v[224:227], v[164:167], v[26:29]
	v_mfma_f32_16x16x32_bf16 v[22:25], v[216:219], v[172:175], v[22:25]
	v_mfma_f32_16x16x32_bf16 v[18:21], v[224:227], v[172:175], v[18:21]
	v_mfma_f32_16x16x32_bf16 v[14:17], v[216:219], v[180:183], v[14:17]
	v_mfma_f32_16x16x32_bf16 v[10:13], v[224:227], v[180:183], v[10:13]
	v_mfma_f32_16x16x32_bf16 v[6:9], v[216:219], v[188:191], v[6:9]
	v_mfma_f32_16x16x32_bf16 v[2:5], v[224:227], v[188:191], v[2:5]
	v_mfma_f32_16x16x32_bf16 v[30:33], v[220:223], v[168:171], v[30:33]
	v_mfma_f32_16x16x32_bf16 v[26:29], v[228:231], v[168:171], v[26:29]
	v_mfma_f32_16x16x32_bf16 v[22:25], v[220:223], v[176:179], v[22:25]
	v_mfma_f32_16x16x32_bf16 v[18:21], v[228:231], v[176:179], v[18:21]
	v_mfma_f32_16x16x32_bf16 v[14:17], v[220:223], v[184:187], v[14:17]
	v_mfma_f32_16x16x32_bf16 v[10:13], v[228:231], v[184:187], v[10:13]
	v_mfma_f32_16x16x32_bf16 v[6:9], v[220:223], v[192:195], v[6:9]
	v_mfma_f32_16x16x32_bf16 v[2:5], v[228:231], v[192:195], v[2:5]
	s_setprio 0
	s_add_i32 vcc_lo, vcc_lo, 2
	s_add_u32 s12, s12, 0x100
	s_addc_u32 s13, s13, 0
	s_cmp_gt_u32 vcc_lo, 53
	s_barrier
	s_cbranch_scc0 .LBB0_392
	s_cmpk_gt_u32 s85, 0xff
	s_cbranch_scc1 .Lgx_g_pre
	s_barrier
.Lgx_g_pre:
	v_lshl_add_u32 v142, s67, 8, v144
	v_lshl_or_b32 v140, s68, 8, v146
	v_ashrrev_i32_e32 v143, 31, v142
	v_readlane_b32 s2, v250, 17
	v_ashrrev_i32_e32 v141, 31, v140
	v_lshlrev_b64 v[148:149], 11, v[142:143]
	v_readlane_b32 s3, v250, 18
	v_lshlrev_b64 v[152:153], 1, v[140:141]
	v_cvt_pk_bf16_f32 v150, v122, v123
	v_cvt_pk_bf16_f32 v151, v124, v125
	s_add_u32 s12, s78, 0xffffff00
	v_lshl_add_u64 v[148:149], s[2:3], 0, v[148:149]
	v_lshl_add_u64 v[140:141], v[148:149], 0, v[152:153]
	v_cvt_pk_bf16_f32 v148, v126, v127
	v_cvt_pk_bf16_f32 v149, v128, v129
	global_store_dwordx4 v[140:141], v[148:151], off
	s_addc_u32 s13, s79, -1
	s_nop 0
	v_cvt_pk_bf16_f32 v148, v94, v95
	v_cvt_pk_bf16_f32 v149, v96, v97
	v_cvt_pk_bf16_f32 v150, v90, v91
	v_cvt_pk_bf16_f32 v151, v92, v93
	global_store_dwordx4 v[140:141], v[148:151], off offset:256
	s_nop 1
	v_or_b32_e32 v148, 16, v142
	v_ashrrev_i32_e32 v149, 31, v148
	v_lshlrev_b64 v[148:149], 11, v[148:149]
	v_lshl_add_u64 v[148:149], s[2:3], 0, v[148:149]
	v_lshl_add_u64 v[154:155], v[148:149], 0, v[152:153]
	v_cvt_pk_bf16_f32 v148, v118, v119
	v_cvt_pk_bf16_f32 v149, v120, v121
	v_cvt_pk_bf16_f32 v150, v114, v115
	v_cvt_pk_bf16_f32 v151, v116, v117
	global_store_dwordx4 v[154:155], v[148:151], off
	s_nop 1
	v_cvt_pk_bf16_f32 v148, v86, v87
	v_cvt_pk_bf16_f32 v149, v88, v89
	v_cvt_pk_bf16_f32 v150, v82, v83
	v_cvt_pk_bf16_f32 v151, v84, v85
	global_store_dwordx4 v[154:155], v[148:151], off offset:256
	s_nop 1
	v_or_b32_e32 v148, 32, v142
	v_ashrrev_i32_e32 v149, 31, v148
	v_lshlrev_b64 v[148:149], 11, v[148:149]
	v_or_b32_e32 v142, 48, v142
	v_lshl_add_u64 v[148:149], s[2:3], 0, v[148:149]
	v_ashrrev_i32_e32 v143, 31, v142
	v_lshl_add_u64 v[154:155], v[148:149], 0, v[152:153]
	v_cvt_pk_bf16_f32 v148, v110, v111
	v_cvt_pk_bf16_f32 v149, v112, v113
	v_cvt_pk_bf16_f32 v150, v106, v107
	v_cvt_pk_bf16_f32 v151, v108, v109
	v_lshlrev_b64 v[142:143], 11, v[142:143]
	global_store_dwordx4 v[154:155], v[148:151], off
	v_lshl_add_u64 v[142:143], s[2:3], 0, v[142:143]
	v_lshl_add_u64 v[142:143], v[142:143], 0, v[152:153]
	v_cvt_pk_bf16_f32 v148, v78, v79
	v_cvt_pk_bf16_f32 v149, v80, v81
	v_cvt_pk_bf16_f32 v150, v74, v75
	v_cvt_pk_bf16_f32 v151, v76, v77
	global_store_dwordx4 v[154:155], v[148:151], off offset:256
	s_mov_b64 s[2:3], 0x40000
; __device__ __forceinline__ unsigned pk2(float lo, float hi) { unsigned r; asm("v_cvt_pk_bf16_f32 %0, %1, %2" : "=v"(r) : "v"(lo), "v"(hi)); return r; }
; #define PG8_WAIT_V(n) asm volatile("s_waitcnt vmcnt(" #n ")" ::: "memory")
; #define PG8_BAR __builtin_amdgcn_s_barrier()
; template <class Epi, class Sched>
; __device__ __forceinline__ void gemm_phase(LAS unsigned char* lds, const int K, const int lda, const int ldb, const Sched& S, const Epi& E) {
;     ...
;         if (!has_next) break;
; #pragma unroll
;         for (int a = 0; a < 2; ++a)
; #pragma unroll
;             for (int b = 0; b < 2; ++b)
; #pragma unroll
;                 for (int m = 0; m < 4; ++m)
; #pragma unroll
;                     for (int n = 0; n < 2; ++n) acc[a][b][m][n] = (f32x4){0.f, 0.f, 0.f, 0.f};
;         cur = nxt; cA = nA; cB = nB; ++ui;
;     }
;     PG8_WAIT_V(0);
;     if (wr == 0) PG8_BAR;
;     PG8_BAR;
;     __device__ __forceinline__ void operator()(const Acc& acc, const Unit& u, int wr, int wc, int fr, int fq) const {
;     ...
;             for (int m = 0; m < 4; ++m) { bf16_t* rp = O + (size_t)(row0 + ai * HALF + m * 16) * ld + col0;
; #pragma unroll
;                 for (int bj = 0; bj < 2; ++bj) { const f32x4 v0 = acc[ai][bj][m][0], v1 = acc[ai][bj][m][1];
;                     u32x4 o; o.x = pk2(v0[0], v0[1]); o.y = pk2(v0[2], v0[3]); o.z = pk2(v1[0], v1[1]); o.w = pk2(v1[2], v1[3]);
;                     *(u32x4*)(rp + bj * HALF) = o; } }
	s_nop 0
	v_cvt_pk_bf16_f32 v148, v102, v103
	v_cvt_pk_bf16_f32 v149, v104, v105
	v_cvt_pk_bf16_f32 v150, v98, v99
	v_cvt_pk_bf16_f32 v151, v100, v101
	global_store_dwordx4 v[142:143], v[148:151], off
	s_nop 1
	v_cvt_pk_bf16_f32 v148, v70, v71
	v_cvt_pk_bf16_f32 v149, v72, v73
	v_cvt_pk_bf16_f32 v150, v66, v67
	v_cvt_pk_bf16_f32 v151, v68, v69
	global_store_dwordx4 v[142:143], v[148:151], off offset:256
	v_lshl_add_u64 v[142:143], v[140:141], 0, s[2:3]
	s_mov_b32 s2, 0x40000
	v_add_co_u32_e32 v152, vcc, s2, v140
	v_cvt_pk_bf16_f32 v148, v62, v63
	v_cvt_pk_bf16_f32 v149, v64, v65
	v_cvt_pk_bf16_f32 v150, v58, v59
	v_cvt_pk_bf16_f32 v151, v60, v61
	s_nop 1
	v_addc_co_u32_e32 v153, vcc, 0, v141, vcc
	global_store_dwordx4 v[152:153], v[148:151], off
	s_mov_b64 s[2:3], 0x48000
	v_add_co_u32_e32 v152, vcc, s43, v140
	v_cvt_pk_bf16_f32 v148, v30, v31
	v_cvt_pk_bf16_f32 v149, v32, v33
	v_cvt_pk_bf16_f32 v150, v26, v27
	v_cvt_pk_bf16_f32 v151, v28, v29
	global_store_dwordx4 v[142:143], v[148:151], off offset:256
	v_lshl_add_u64 v[142:143], v[140:141], 0, s[2:3]
	v_addc_co_u32_e32 v153, vcc, 0, v141, vcc
	v_cvt_pk_bf16_f32 v148, v54, v55
	v_cvt_pk_bf16_f32 v149, v56, v57
	v_cvt_pk_bf16_f32 v150, v50, v51
	v_cvt_pk_bf16_f32 v151, v52, v53
	s_mov_b64 s[2:3], 0x50000
	global_store_dwordx4 v[152:153], v[148:151], off
	s_nop 1
	v_cvt_pk_bf16_f32 v148, v22, v23
	v_cvt_pk_bf16_f32 v149, v24, v25
	v_cvt_pk_bf16_f32 v150, v18, v19
	v_cvt_pk_bf16_f32 v151, v20, v21
	global_store_dwordx4 v[142:143], v[148:151], off offset:256
	v_lshl_add_u64 v[142:143], v[140:141], 0, s[2:3]
	s_mov_b32 s2, 0x50000
	v_add_co_u32_e32 v152, vcc, s2, v140
	s_mov_b64 s[2:3], 0x58000
	s_nop 0
	v_addc_co_u32_e32 v153, vcc, 0, v141, vcc
	v_cvt_pk_bf16_f32 v148, v46, v47
	v_cvt_pk_bf16_f32 v149, v48, v49
	v_cvt_pk_bf16_f32 v150, v42, v43
	v_cvt_pk_bf16_f32 v151, v44, v45
	global_store_dwordx4 v[152:153], v[148:151], off
	v_lshl_add_u64 v[152:153], v[140:141], 0, s[2:3]
	s_mov_b32 s2, 0x58000
	v_add_co_u32_e32 v140, vcc, s2, v140
	v_cvt_pk_bf16_f32 v148, v14, v15
	v_cvt_pk_bf16_f32 v149, v16, v17
	v_cvt_pk_bf16_f32 v150, v10, v11
	v_cvt_pk_bf16_f32 v151, v12, v13
	s_nop 1
	v_addc_co_u32_e32 v141, vcc, 0, v141, vcc
	s_andn2_b64 vcc, exec, s[8:9]
	global_store_dwordx4 v[142:143], v[148:151], off offset:256
	v_cvt_pk_bf16_f32 v142, v2, v3
	v_cvt_pk_bf16_f32 v143, v4, v5
	s_nop 1
	v_cvt_pk_bf16_f32 v148, v38, v39
	v_cvt_pk_bf16_f32 v149, v40, v41
	v_cvt_pk_bf16_f32 v150, v34, v35
	v_cvt_pk_bf16_f32 v151, v36, v37
	global_store_dwordx4 v[140:141], v[148:151], off
	v_cvt_pk_bf16_f32 v140, v6, v7
	v_cvt_pk_bf16_f32 v141, v8, v9
	global_store_dwordx4 v[152:153], v[140:143], off offset:256
	s_cbranch_vccnz .LBB0_383
	v_mov_b32_e32 v2, 0
	s_mov_b32 s68, s76
	s_mov_b32 s67, s75
	s_mov_b64 s[0:1], s[10:11]
	s_mov_b32 s73, s77
	v_mov_b32_e32 v3, v2
	v_mov_b64_e32 v[4:5], 0
	v_mov_b64_e32 v[6:7], 0
	v_mov_b64_e32 v[8:9], 0
	v_mov_b64_e32 v[10:11], 0
	v_mov_b64_e32 v[12:13], 0
	v_mov_b64_e32 v[14:15], 0
	v_mov_b64_e32 v[16:17], 0
	v_mov_b64_e32 v[18:19], 0
	v_mov_b64_e32 v[20:21], 0
	v_mov_b64_e32 v[22:23], 0
	v_mov_b64_e32 v[24:25], 0
	v_mov_b64_e32 v[26:27], 0
	v_mov_b64_e32 v[28:29], 0
	v_mov_b64_e32 v[30:31], 0
	v_mov_b64_e32 v[32:33], 0
	v_mov_b64_e32 v[34:35], 0
	v_mov_b64_e32 v[36:37], 0
	v_mov_b64_e32 v[38:39], 0
	v_mov_b64_e32 v[40:41], 0
	v_mov_b64_e32 v[42:43], 0
	v_mov_b64_e32 v[44:45], 0
	v_mov_b64_e32 v[46:47], 0
	v_mov_b64_e32 v[48:49], 0
	v_mov_b64_e32 v[50:51], 0
	v_mov_b64_e32 v[52:53], 0
	v_mov_b64_e32 v[54:55], 0
	v_mov_b64_e32 v[56:57], 0
	v_mov_b64_e32 v[58:59], 0
	v_mov_b64_e32 v[60:61], 0
	v_mov_b64_e32 v[62:63], 0
	v_mov_b64_e32 v[64:65], 0
	v_mov_b64_e32 v[66:67], 0
	v_mov_b64_e32 v[68:69], 0
	v_mov_b64_e32 v[70:71], 0
	v_mov_b64_e32 v[72:73], 0
	v_mov_b64_e32 v[74:75], 0
	v_mov_b64_e32 v[76:77], 0
	v_mov_b64_e32 v[78:79], 0
	v_mov_b64_e32 v[80:81], 0
	v_mov_b64_e32 v[82:83], 0
	v_mov_b64_e32 v[84:85], 0
	v_mov_b64_e32 v[86:87], 0
	v_mov_b64_e32 v[88:89], 0
	v_mov_b64_e32 v[90:91], 0
	v_mov_b64_e32 v[92:93], 0
	v_mov_b64_e32 v[94:95], 0
	v_mov_b64_e32 v[96:97], 0
	v_mov_b64_e32 v[98:99], 0
	v_mov_b64_e32 v[100:101], 0
	v_mov_b64_e32 v[102:103], 0
	v_mov_b64_e32 v[104:105], 0
	v_mov_b64_e32 v[106:107], 0
	v_mov_b64_e32 v[108:109], 0
	v_mov_b64_e32 v[110:111], 0
	v_mov_b64_e32 v[112:113], 0
	v_mov_b64_e32 v[114:115], 0
	v_mov_b64_e32 v[116:117], 0
	v_mov_b64_e32 v[118:119], 0
	v_mov_b64_e32 v[120:121], 0
	v_mov_b64_e32 v[122:123], 0
	v_mov_b64_e32 v[124:125], 0
	v_mov_b64_e32 v[126:127], 0
	v_mov_b64_e32 v[128:129], 0
	s_cmpk_gt_u32 s85, 0xff
	s_cbranch_scc0 .LBB0_384
	s_barrier
	s_branch .LBB0_384
.LBB0_395:
	s_waitcnt vmcnt(0)
.LBB0_397:
	v_readlane_b32 s52, v253, 11
	v_readlane_b32 s54, v253, 13
	v_readlane_b32 s70, v253, 15
	v_readlane_b32 s66, v253, 17
	v_readlane_b32 s83, v253, 4
	v_readlane_b32 s84, v253, 5
	v_readlane_b32 s75, v253, 6
	v_readlane_b32 s53, v253, 12
	v_readlane_b32 s55, v253, 14
	v_readlane_b32 s71, v253, 16
	v_readlane_b32 s67, v253, 18
	v_readlane_b32 s69, v253, 21
	s_movk_i32 s62, 0x14ff
	s_movk_i32 s48, 0x7000
	s_mov_b32 s68, 0x48000
	s_movk_i32 s45, 0x3fff
	s_mov_b32 s47, s94
	s_barrier

; template <class Epi, class Sched>
; __device__ __forceinline__ void gemm_phase(LAS unsigned char* lds, const int K, const int lda, const int ldb, const Sched& S, const Epi& E) {
;     ...
;         if constexpr (!Epi::AFTER_DRAIN) E(acc, cur, wr, wc, fr, fq);
;         if (!has_next) break;
; #pragma unroll
;         for (int a = 0; a < 2; ++a)
; #pragma unroll
;             for (int b = 0; b < 2; ++b)
; #pragma unroll
;                 for (int m = 0; m < 4; ++m)
; #pragma unroll
;                     for (int n = 0; n < 2; ++n) acc[a][b][m][n] = (f32x4){0.f, 0.f, 0.f, 0.f};
;         cur = nxt; cA = nA; cB = nB; ++ui;
.LBB0_965:
	s_and_b64 vcc, exec, s[4:5]
	s_mov_b32 s37, s6
	s_mov_b32 s0, s8
	s_mov_b64 s[16:17], s[12:13]
	s_mov_b64 s[14:15], s[10:11]
	global_store_dwordx4 v[2:3], v[6:9], off
	s_cbranch_vccnz .LBB0_1034
	s_cmpk_gt_u32 s36, 0xff
	s_cbranch_scc0 .LBB0_966
	s_barrier

; #define PG8_STAGE(bufoff, gbase, voff) do { _Pragma("unroll") for (int _i = 0; _i < 2; ++_i) \
;         __builtin_amdgcn_global_load_lds((const unsigned*)((const char*)(gbase) + (voff)[_i]), (LAS unsigned*)(lds + (bufoff) + ldsw + _i * 8192), 16, 0, 0); } while (0)
; #define PG8_STAGE_A(bufoff, gbase, h, vv) do { if constexpr (GATHER) { _Pragma("unroll") for (int _i = 0; _i < 2; ++_i) \
;         __builtin_amdgcn_global_load_lds((const unsigned*)((const char*)(gbase) + (vv)[h][_i]), (LAS unsigned*)(lds + (bufoff) + ldsw + _i * 8192), 16, 0, 0); } \
;         else { PG8_STAGE(bufoff, (gbase) + (h) * hstepA, voffA); } } while (0)
; #define PG8_LDA(dst, b, h) do { _Pragma("unroll") for (int m = 0; m < 4; ++m) _Pragma("unroll") for (int k = 0; k < 2; ++k) dst[m][k] = *(const LAS bf16x8*)(lds + PG8_SA(b, h) + aoff + m * 2048 + k * 1024); } while (0)
; #define PG8_LDB(dst, b, h) do { _Pragma("unroll") for (int n = 0; n < 2; ++n) _Pragma("unroll") for (int k = 0; k < 2; ++k) dst[n][k] = *(const LAS bf16x8*)(lds + PG8_SB(b, h) + boff + n * 2048 + k * 1024); } while (0)
; #define PG8_WAIT_L(n) asm volatile("s_waitcnt lgkmcnt(" #n ")" ::: "memory")
; template <class Epi, class Sched>
; __device__ __forceinline__ void gemm_phase(LAS unsigned char* lds, const int K, const int lda, const int ldb, const Sched& S, const Epi& E) {
;     ...
;         for (int t = 0; t < nt; t += 2) {
;             const bool last = (t == nt - 2);
;             const char* a1 = cA + (size_t)(t + 1) * kstep;
;             const char* a2 = last ? nA : cA + (size_t)(t + 2) * kstep; const char* b2 = last ? nB : cB + (size_t)(t + 2) * kstep;
;             const char* a3 = a2 + kstep; const char* b3 = b2 + kstep;
;             PG8_LDB(B0, 0, 0); PG8_SCHED; PG8_LDA(At, 0, 0); PG8_STAGE_A(PG8_SA(1, 1), a1, 1, vcur);
;             if constexpr (GATHER) { if (last) {
; #pragma unroll
;                 for (int h = 0; h < 2; ++h)
; #pragma unroll
;                     for (int i = 0; i < 2; ++i) vcur[h][i] = vnxt[h][i]; } }
;             PG8_WAIT_L(8); PG8_BAR; PG8_WAIT_L(0); PG8_MMA(0, 0, At, B0); PG8_BAR; PG8_SCHED;
;             PG8_LDB(B1, 0, 1); PG8_STAGE(PG8_SB(0, 0), b2, voffB);
;             PG8_BAR; PG8_WAIT_L(0); PG8_MMA(0, 1, At, B1); PG8_BAR;
;             PG8_LDA(At, 0, 1); PG8_STAGE_A(PG8_SA(0, 0), a2, 0, vcur);
;             PG8_BAR; PG8_WAIT_L(0); PG8_MMA(1, 0, At, B0); PG8_BAR; PG8_SCHED;
.LBB0_969:
	s_add_u32 s2, s14, 0xfffc0080
	s_addc_u32 s3, s15, -1
	s_add_i32 s48, 0, 0x10000
	v_add_u32_e32 v0, s48, v146
	ds_read_b128 v[148:151], v0
	ds_read_b128 v[152:155], v0 offset:1024
	ds_read_b128 v[156:159], v0 offset:2048
	ds_read_b128 v[160:163], v0 offset:3072
	s_cmp_eq_u32 s9, 12
	s_cselect_b32 s19, s11, s3
	s_cselect_b32 s18, s10, s2
	s_cselect_b32 s17, s13, s7
	s_cselect_b32 s16, s12, s1
	v_lshl_add_u64 v[144:145], s[14:15], 0, v[140:141]
	s_add_i32 m0, s39, 0xc000
	ds_read_b128 v[164:167], v147
	ds_read_b128 v[168:171], v147 offset:1024
	ds_read_b128 v[172:175], v147 offset:2048
	ds_read_b128 v[176:179], v147 offset:3072
	ds_read_b128 v[180:183], v147 offset:4096
	ds_read_b128 v[184:187], v147 offset:5120
	ds_read_b128 v[188:191], v147 offset:6144
	ds_read_b128 v[192:195], v147 offset:7168
	global_load_lds_dwordx4 v[144:145], off
	v_lshl_add_u64 v[144:145], s[14:15], 0, v[142:143]
	s_add_i32 m0, s39, 0xe000
	s_nop 0
	global_load_lds_dwordx4 v[144:145], off
	s_waitcnt lgkmcnt(8)
	s_barrier
	s_waitcnt lgkmcnt(0)
	s_setprio 1
	s_waitcnt lgkmcnt(0)
	v_mfma_f32_16x16x32_bf16 v[126:129], v[148:151], v[164:167], v[126:129]
	v_mfma_f32_16x16x32_bf16 v[122:125], v[156:159], v[164:167], v[122:125]
	v_mfma_f32_16x16x32_bf16 v[110:113], v[148:151], v[172:175], v[110:113]
	v_mfma_f32_16x16x32_bf16 v[106:109], v[156:159], v[172:175], v[106:109]
	v_mfma_f32_16x16x32_bf16 v[94:97], v[148:151], v[180:183], v[94:97]
	v_mfma_f32_16x16x32_bf16 v[90:93], v[156:159], v[180:183], v[90:93]
	v_mfma_f32_16x16x32_bf16 v[78:81], v[148:151], v[188:191], v[78:81]
	v_mfma_f32_16x16x32_bf16 v[74:77], v[156:159], v[188:191], v[74:77]
	v_mfma_f32_16x16x32_bf16 v[126:129], v[152:155], v[168:171], v[126:129]
	v_mfma_f32_16x16x32_bf16 v[122:125], v[160:163], v[168:171], v[122:125]
	v_mfma_f32_16x16x32_bf16 v[110:113], v[152:155], v[176:179], v[110:113]
	v_mfma_f32_16x16x32_bf16 v[106:109], v[160:163], v[176:179], v[106:109]
	v_mfma_f32_16x16x32_bf16 v[94:97], v[152:155], v[184:187], v[94:97]
	v_mfma_f32_16x16x32_bf16 v[90:93], v[160:163], v[184:187], v[90:93]
	v_mfma_f32_16x16x32_bf16 v[78:81], v[152:155], v[192:195], v[78:81]
	v_mfma_f32_16x16x32_bf16 v[74:77], v[160:163], v[192:195], v[74:77]
	s_setprio 0
	s_barrier
	s_add_i32 s2, 0, 0x14000
	s_add_i32 s3, s48, s38
	v_add_u32_e32 v0, s2, v146
	v_lshl_add_u64 v[144:145], s[16:17], 0, v[132:133]
	s_mov_b32 m0, s3
	ds_read_b128 v[216:219], v0
	ds_read_b128 v[220:223], v0 offset:1024
	ds_read_b128 v[224:227], v0 offset:2048
	ds_read_b128 v[228:231], v0 offset:3072
	global_load_lds_dwordx4 v[144:145], off
	v_lshl_add_u64 v[232:233], s[16:17], 0, v[136:137]
	s_add_i32 m0, s3, 0x2000
	s_nop 0
	global_load_lds_dwordx4 v[232:233], off
	s_barrier
	s_waitcnt lgkmcnt(0)
	s_setprio 1
	s_waitcnt lgkmcnt(0)
	v_mfma_f32_16x16x32_bf16 v[118:121], v[216:219], v[164:167], v[118:121]
	v_mfma_f32_16x16x32_bf16 v[114:117], v[224:227], v[164:167], v[114:117]
	v_mfma_f32_16x16x32_bf16 v[102:105], v[216:219], v[172:175], v[102:105]
	v_mfma_f32_16x16x32_bf16 v[98:101], v[224:227], v[172:175], v[98:101]
	v_mfma_f32_16x16x32_bf16 v[86:89], v[216:219], v[180:183], v[86:89]
	v_mfma_f32_16x16x32_bf16 v[82:85], v[224:227], v[180:183], v[82:85]
	v_mfma_f32_16x16x32_bf16 v[70:73], v[216:219], v[188:191], v[70:73]
	v_mfma_f32_16x16x32_bf16 v[66:69], v[224:227], v[188:191], v[66:69]
	v_mfma_f32_16x16x32_bf16 v[118:121], v[220:223], v[168:171], v[118:121]
	v_mfma_f32_16x16x32_bf16 v[114:117], v[228:231], v[168:171], v[114:117]
	v_mfma_f32_16x16x32_bf16 v[102:105], v[220:223], v[176:179], v[102:105]
	v_mfma_f32_16x16x32_bf16 v[98:101], v[228:231], v[176:179], v[98:101]
	v_mfma_f32_16x16x32_bf16 v[86:89], v[220:223], v[184:187], v[86:89]
	v_mfma_f32_16x16x32_bf16 v[82:85], v[228:231], v[184:187], v[82:85]
	v_mfma_f32_16x16x32_bf16 v[70:73], v[220:223], v[192:195], v[70:73]
	v_mfma_f32_16x16x32_bf16 v[66:69], v[228:231], v[192:195], v[66:69]
	s_setprio 0
	s_mov_b32 m0, s39
	v_lshl_add_u64 v[234:235], s[18:19], 0, v[130:131]
	s_barrier
	ds_read_b128 v[164:167], v147 offset:16384
	ds_read_b128 v[168:171], v147 offset:17408
	ds_read_b128 v[172:175], v147 offset:18432
	ds_read_b128 v[176:179], v147 offset:19456
	ds_read_b128 v[180:183], v147 offset:20480
	ds_read_b128 v[184:187], v147 offset:21504
	ds_read_b128 v[188:191], v147 offset:22528
	ds_read_b128 v[192:195], v147 offset:23552
	global_load_lds_dwordx4 v[234:235], off
	v_lshl_add_u64 v[236:237], s[18:19], 0, v[134:135]
	s_mov_b32 m0, s40
	s_nop 0
	global_load_lds_dwordx4 v[236:237], off
	s_barrier
	s_waitcnt lgkmcnt(0)
	s_setprio 1
	s_waitcnt lgkmcnt(0)
	v_mfma_f32_16x16x32_bf16 v[62:65], v[148:151], v[164:167], v[62:65]
	v_mfma_f32_16x16x32_bf16 v[58:61], v[156:159], v[164:167], v[58:61]
	v_mfma_f32_16x16x32_bf16 v[46:49], v[148:151], v[172:175], v[46:49]
	v_mfma_f32_16x16x32_bf16 v[42:45], v[156:159], v[172:175], v[42:45]
	v_mfma_f32_16x16x32_bf16 v[30:33], v[148:151], v[180:183], v[30:33]
	v_mfma_f32_16x16x32_bf16 v[26:29], v[156:159], v[180:183], v[26:29]
	v_mfma_f32_16x16x32_bf16 v[14:17], v[148:151], v[188:191], v[14:17]
	v_mfma_f32_16x16x32_bf16 v[10:13], v[156:159], v[188:191], v[10:13]
	v_mfma_f32_16x16x32_bf16 v[62:65], v[152:155], v[168:171], v[62:65]
	v_mfma_f32_16x16x32_bf16 v[58:61], v[160:163], v[168:171], v[58:61]
	v_mfma_f32_16x16x32_bf16 v[46:49], v[152:155], v[176:179], v[46:49]
	v_mfma_f32_16x16x32_bf16 v[42:45], v[160:163], v[176:179], v[42:45]
	v_mfma_f32_16x16x32_bf16 v[30:33], v[152:155], v[184:187], v[30:33]
	v_mfma_f32_16x16x32_bf16 v[26:29], v[160:163], v[184:187], v[26:29]
	v_mfma_f32_16x16x32_bf16 v[14:17], v[152:155], v[192:195], v[14:17]
	v_mfma_f32_16x16x32_bf16 v[10:13], v[160:163], v[192:195], v[10:13]
	s_setprio 0
	s_barrier
; #define PG8_STAGE(bufoff, gbase, voff) do { _Pragma("unroll") for (int _i = 0; _i < 2; ++_i) \
;         __builtin_amdgcn_global_load_lds((const unsigned*)((const char*)(gbase) + (voff)[_i]), (LAS unsigned*)(lds + (bufoff) + ldsw + _i * 8192), 16, 0, 0); } while (0)
; #define PG8_STAGE_A(bufoff, gbase, h, vv) do { if constexpr (GATHER) { _Pragma("unroll") for (int _i = 0; _i < 2; ++_i) \
;         __builtin_amdgcn_global_load_lds((const unsigned*)((const char*)(gbase) + (vv)[h][_i]), (LAS unsigned*)(lds + (bufoff) + ldsw + _i * 8192), 16, 0, 0); } \
;         else { PG8_STAGE(bufoff, (gbase) + (h) * hstepA, voffA); } } while (0)
; #define PG8_LDA(dst, b, h) do { _Pragma("unroll") for (int m = 0; m < 4; ++m) _Pragma("unroll") for (int k = 0; k < 2; ++k) dst[m][k] = *(const LAS bf16x8*)(lds + PG8_SA(b, h) + aoff + m * 2048 + k * 1024); } while (0)
; #define PG8_LDB(dst, b, h) do { _Pragma("unroll") for (int n = 0; n < 2; ++n) _Pragma("unroll") for (int k = 0; k < 2; ++k) dst[n][k] = *(const LAS bf16x8*)(lds + PG8_SB(b, h) + boff + n * 2048 + k * 1024); } while (0)
; #define PG8_MMA(ai, bj, At, Bt) do { __builtin_amdgcn_s_setprio(1); _Pragma("unroll") for (int m = 0; m < 4; ++m) _Pragma("unroll") for (int n = 0; n < 2; ++n) _Pragma("unroll") for (int k = 0; k < 2; ++k) \
;         acc[ai][bj][m][n] = __builtin_amdgcn_mfma_f32_16x16x32_bf16(Bt[n][k], At[m][k], acc[ai][bj][m][n], 0, 0, 0); __builtin_amdgcn_s_setprio(0); } while (0)
; #define PG8_WAIT_V(n) asm volatile("s_waitcnt vmcnt(" #n ")" ::: "memory")
; #define PG8_WAIT_L(n) asm volatile("s_waitcnt lgkmcnt(" #n ")" ::: "memory")
; #define PG8_BAR __builtin_amdgcn_s_barrier()
; template <class Epi, class Sched>
; __device__ __forceinline__ void gemm_phase(LAS unsigned char* lds, const int K, const int lda, const int ldb, const Sched& S, const Epi& E) {
;     ...
;             PG8_STAGE(PG8_SB(0, 1), b2 + hstepB, voffB);
;             PG8_WAIT_V(6); PG8_BAR; PG8_MMA(1, 1, At, B1); PG8_BAR;
;             PG8_LDB(B0, 1, 0); PG8_SCHED; PG8_LDA(At, 1, 0); PG8_STAGE_A(PG8_SA(0, 1), a2, 1, vcur);
;             PG8_WAIT_L(8); PG8_BAR; PG8_WAIT_L(0); PG8_MMA(0, 0, At, B0); PG8_BAR; PG8_SCHED;
;             PG8_LDB(B1, 1, 1); PG8_STAGE(PG8_SB(1, 0), b3, voffB);
;             PG8_BAR; PG8_WAIT_L(0); PG8_MMA(0, 1, At, B1); PG8_BAR;
;             PG8_LDA(At, 1, 1); PG8_STAGE_A(PG8_SA(1, 0), a3, 0, vcur);
	s_add_u32 s48, s16, 0x40000
	s_addc_u32 s49, s17, 0
	s_add_i32 s2, s2, s38
	v_lshl_add_u64 v[148:149], s[48:49], 0, v[132:133]
	s_mov_b32 m0, s2
	s_nop 0
	global_load_lds_dwordx4 v[148:149], off
	v_lshl_add_u64 v[148:149], s[48:49], 0, v[136:137]
	s_add_i32 m0, s2, 0x2000
	s_nop 0
	global_load_lds_dwordx4 v[148:149], off
	s_waitcnt vmcnt(6)
	s_barrier
	s_setprio 1
	v_mfma_f32_16x16x32_bf16 v[54:57], v[216:219], v[164:167], v[54:57]
	v_mfma_f32_16x16x32_bf16 v[50:53], v[224:227], v[164:167], v[50:53]
	v_mfma_f32_16x16x32_bf16 v[38:41], v[216:219], v[172:175], v[38:41]
	v_mfma_f32_16x16x32_bf16 v[34:37], v[224:227], v[172:175], v[34:37]
	v_mfma_f32_16x16x32_bf16 v[22:25], v[216:219], v[180:183], v[22:25]
	v_mfma_f32_16x16x32_bf16 v[18:21], v[224:227], v[180:183], v[18:21]
	v_mfma_f32_16x16x32_bf16 v[6:9], v[216:219], v[188:191], v[6:9]
	v_mfma_f32_16x16x32_bf16 v[2:5], v[224:227], v[188:191], v[2:5]
	v_mfma_f32_16x16x32_bf16 v[54:57], v[220:223], v[168:171], v[54:57]
	v_mfma_f32_16x16x32_bf16 v[50:53], v[228:231], v[168:171], v[50:53]
	v_mfma_f32_16x16x32_bf16 v[38:41], v[220:223], v[176:179], v[38:41]
	v_mfma_f32_16x16x32_bf16 v[34:37], v[228:231], v[176:179], v[34:37]
	v_mfma_f32_16x16x32_bf16 v[22:25], v[220:223], v[184:187], v[22:25]
	v_mfma_f32_16x16x32_bf16 v[18:21], v[228:231], v[184:187], v[18:21]
	v_mfma_f32_16x16x32_bf16 v[6:9], v[220:223], v[192:195], v[6:9]
	v_mfma_f32_16x16x32_bf16 v[2:5], v[228:231], v[192:195], v[2:5]
	s_setprio 0
	s_add_i32 s2, 0, 0x18000
	v_add_u32_e32 v0, s2, v146
	s_barrier
	ds_read_b128 v[148:151], v0
	ds_read_b128 v[152:155], v0 offset:1024
	ds_read_b128 v[156:159], v0 offset:2048
	ds_read_b128 v[160:163], v0 offset:3072
	s_add_u32 s18, s18, 0x40000
	s_addc_u32 s19, s19, 0
	s_mov_b32 m0, s41
	v_lshl_add_u64 v[216:217], s[18:19], 0, v[130:131]
	ds_read_b128 v[164:167], v147 offset:32768
	ds_read_b128 v[168:171], v147 offset:33792
	ds_read_b128 v[172:175], v147 offset:34816
	ds_read_b128 v[176:179], v147 offset:35840
	ds_read_b128 v[180:183], v147 offset:36864
	ds_read_b128 v[184:187], v147 offset:37888
	ds_read_b128 v[188:191], v147 offset:38912
	ds_read_b128 v[192:195], v147 offset:39936
	global_load_lds_dwordx4 v[216:217], off
	v_lshl_add_u64 v[216:217], s[18:19], 0, v[134:135]
	s_mov_b32 m0, s42
	s_nop 0
	global_load_lds_dwordx4 v[216:217], off
	s_waitcnt lgkmcnt(8)
	s_barrier
	s_waitcnt lgkmcnt(0)
	s_setprio 1
	s_waitcnt lgkmcnt(0)
	v_mfma_f32_16x16x32_bf16 v[126:129], v[148:151], v[164:167], v[126:129]
	v_mfma_f32_16x16x32_bf16 v[122:125], v[156:159], v[164:167], v[122:125]
	v_mfma_f32_16x16x32_bf16 v[110:113], v[148:151], v[172:175], v[110:113]
	v_mfma_f32_16x16x32_bf16 v[106:109], v[156:159], v[172:175], v[106:109]
	v_mfma_f32_16x16x32_bf16 v[94:97], v[148:151], v[180:183], v[94:97]
	v_mfma_f32_16x16x32_bf16 v[90:93], v[156:159], v[180:183], v[90:93]
	v_mfma_f32_16x16x32_bf16 v[78:81], v[148:151], v[188:191], v[78:81]
	v_mfma_f32_16x16x32_bf16 v[74:77], v[156:159], v[188:191], v[74:77]
	v_mfma_f32_16x16x32_bf16 v[126:129], v[152:155], v[168:171], v[126:129]
	v_mfma_f32_16x16x32_bf16 v[122:125], v[160:163], v[168:171], v[122:125]
	v_mfma_f32_16x16x32_bf16 v[110:113], v[152:155], v[176:179], v[110:113]
	v_mfma_f32_16x16x32_bf16 v[106:109], v[160:163], v[176:179], v[106:109]
	v_mfma_f32_16x16x32_bf16 v[94:97], v[152:155], v[184:187], v[94:97]
	v_mfma_f32_16x16x32_bf16 v[90:93], v[160:163], v[184:187], v[90:93]
	v_mfma_f32_16x16x32_bf16 v[78:81], v[152:155], v[192:195], v[78:81]
	v_mfma_f32_16x16x32_bf16 v[74:77], v[160:163], v[192:195], v[74:77]
	s_setprio 0
	s_barrier
	s_add_i32 s3, 0, 0x1c000
	s_add_i32 s2, s2, s38
	v_add_u32_e32 v0, s3, v146
	v_lshl_add_u64 v[144:145], v[144:145], 0, s[64:65]
	s_mov_b32 m0, s2
	ds_read_b128 v[216:219], v0
	ds_read_b128 v[220:223], v0 offset:1024
	ds_read_b128 v[224:227], v0 offset:2048
	ds_read_b128 v[228:231], v0 offset:3072
	global_load_lds_dwordx4 v[144:145], off
	v_lshl_add_u64 v[144:145], v[232:233], 0, s[64:65]
	s_add_i32 m0, s2, 0x2000
	s_nop 0
	global_load_lds_dwordx4 v[144:145], off
	s_barrier
	s_waitcnt lgkmcnt(0)
	s_setprio 1
	s_waitcnt lgkmcnt(0)
	v_mfma_f32_16x16x32_bf16 v[118:121], v[216:219], v[164:167], v[118:121]
	v_mfma_f32_16x16x32_bf16 v[114:117], v[224:227], v[164:167], v[114:117]
	v_mfma_f32_16x16x32_bf16 v[102:105], v[216:219], v[172:175], v[102:105]
	v_mfma_f32_16x16x32_bf16 v[98:101], v[224:227], v[172:175], v[98:101]
	v_mfma_f32_16x16x32_bf16 v[86:89], v[216:219], v[180:183], v[86:89]
	v_mfma_f32_16x16x32_bf16 v[82:85], v[224:227], v[180:183], v[82:85]
	v_mfma_f32_16x16x32_bf16 v[70:73], v[216:219], v[188:191], v[70:73]
	v_mfma_f32_16x16x32_bf16 v[66:69], v[224:227], v[188:191], v[66:69]
	v_mfma_f32_16x16x32_bf16 v[118:121], v[220:223], v[168:171], v[118:121]
	v_mfma_f32_16x16x32_bf16 v[114:117], v[228:231], v[168:171], v[114:117]
	v_mfma_f32_16x16x32_bf16 v[102:105], v[220:223], v[176:179], v[102:105]
	v_mfma_f32_16x16x32_bf16 v[98:101], v[228:231], v[176:179], v[98:101]
	v_mfma_f32_16x16x32_bf16 v[86:89], v[220:223], v[184:187], v[86:89]
	v_mfma_f32_16x16x32_bf16 v[82:85], v[228:231], v[184:187], v[82:85]
	v_mfma_f32_16x16x32_bf16 v[70:73], v[220:223], v[192:195], v[70:73]
	v_mfma_f32_16x16x32_bf16 v[66:69], v[228:231], v[192:195], v[66:69]
	s_setprio 0
	s_mov_b32 m0, s44
	v_lshl_add_u64 v[144:145], v[234:235], 0, s[64:65]
	s_barrier
; __device__ __forceinline__ unsigned pk2(float lo, float hi) { unsigned r; asm("v_cvt_pk_bf16_f32 %0, %1, %2" : "=v"(r) : "v"(lo), "v"(hi)); return r; }
; #define PG8_STAGE(bufoff, gbase, voff) do { _Pragma("unroll") for (int _i = 0; _i < 2; ++_i) \
;         __builtin_amdgcn_global_load_lds((const unsigned*)((const char*)(gbase) + (voff)[_i]), (LAS unsigned*)(lds + (bufoff) + ldsw + _i * 8192), 16, 0, 0); } while (0)
; #define PG8_MMA(ai, bj, At, Bt) do { __builtin_amdgcn_s_setprio(1); _Pragma("unroll") for (int m = 0; m < 4; ++m) _Pragma("unroll") for (int n = 0; n < 2; ++n) _Pragma("unroll") for (int k = 0; k < 2; ++k) \
;         acc[ai][bj][m][n] = __builtin_amdgcn_mfma_f32_16x16x32_bf16(Bt[n][k], At[m][k], acc[ai][bj][m][n], 0, 0, 0); __builtin_amdgcn_s_setprio(0); } while (0)
; #define PG8_BAR __builtin_amdgcn_s_barrier()
; template <class Epi, class Sched>
; __device__ __forceinline__ void gemm_phase(LAS unsigned char* lds, const int K, const int lda, const int ldb, const Sched& S, const Epi& E) {
;     ...
;             PG8_BAR; PG8_WAIT_L(0); PG8_MMA(1, 0, At, B0); PG8_BAR; PG8_SCHED;
;             PG8_STAGE(PG8_SB(1, 1), b3 + hstepB, voffB);
;             PG8_WAIT_V(6); PG8_BAR; PG8_MMA(1, 1, At, B1); PG8_BAR;
;         }
;         if constexpr (GATHER) { Unit n2; if (has_next && S.next(ui + 2, n2)) ld_ix(n2.pm, ix1); }
;         if constexpr (!Epi::AFTER_DRAIN) E(acc, cur, wr, wc, fr, fq);
;     __device__ __forceinline__ void operator()(const Acc& acc, const Unit& u, int wr, int wc, int fr, int fq) const {
;         const int row0 = u.pm * BM + wr * 64 + fr, col0 = u.pn * BM + wc * 32 + 8 * fq;
; #pragma unroll
;         for (int ai = 0; ai < 2; ++ai)
; #pragma unroll
;             for (int m = 0; m < 4; ++m) { const int np = row0 + ai * HALF + m * 16, c = np >> 10, n = np & 1023;
; #pragma unroll
;                 for (int bj = 0; bj < 2; ++bj) { const int j = col0 + bj * HALF; const f32x4 v0 = acc[ai][bj][m][0], v1 = acc[ai][bj][m][1];
;                     u32x4 o; o.x = pk2(v0[0], v0[1]); o.y = pk2(v0[2], v0[3]); o.z = pk2(v1[0], v1[1]); o.w = pk2(v1[2], v1[3]);
;                     bf16_t* dst;
;                     if (u.pn < SEQ / BM) { const int l1 = j >> 7, l2 = j & 127; dst = Zt + ((size_t)(n * 128 + l1) * 2 + c) * 128 + l2; }
;                     else { const int l = j - SEQ; dst = ZcT + (size_t)(n * 2 + c) * 256 + l; }
	ds_read_b128 v[164:167], v147 offset:49152
	ds_read_b128 v[168:171], v147 offset:50176
	ds_read_b128 v[172:175], v147 offset:51200
	ds_read_b128 v[176:179], v147 offset:52224
	ds_read_b128 v[180:183], v147 offset:53248
	ds_read_b128 v[184:187], v147 offset:54272
	ds_read_b128 v[188:191], v147 offset:55296
	ds_read_b128 v[192:195], v147 offset:56320
	global_load_lds_dwordx4 v[144:145], off
	v_lshl_add_u64 v[144:145], v[236:237], 0, s[64:65]
	s_mov_b32 m0, s45
	s_nop 0
	global_load_lds_dwordx4 v[144:145], off
	s_barrier
	s_waitcnt lgkmcnt(0)
	s_setprio 1
	s_waitcnt lgkmcnt(0)
	v_mfma_f32_16x16x32_bf16 v[62:65], v[148:151], v[164:167], v[62:65]
	v_mfma_f32_16x16x32_bf16 v[58:61], v[156:159], v[164:167], v[58:61]
	v_mfma_f32_16x16x32_bf16 v[46:49], v[148:151], v[172:175], v[46:49]
	v_mfma_f32_16x16x32_bf16 v[42:45], v[156:159], v[172:175], v[42:45]
	v_mfma_f32_16x16x32_bf16 v[30:33], v[148:151], v[180:183], v[30:33]
	v_mfma_f32_16x16x32_bf16 v[26:29], v[156:159], v[180:183], v[26:29]
	v_mfma_f32_16x16x32_bf16 v[14:17], v[148:151], v[188:191], v[14:17]
	v_mfma_f32_16x16x32_bf16 v[10:13], v[156:159], v[188:191], v[10:13]
	v_mfma_f32_16x16x32_bf16 v[62:65], v[152:155], v[168:171], v[62:65]
	v_mfma_f32_16x16x32_bf16 v[58:61], v[160:163], v[168:171], v[58:61]
	v_mfma_f32_16x16x32_bf16 v[46:49], v[152:155], v[176:179], v[46:49]
	v_mfma_f32_16x16x32_bf16 v[42:45], v[160:163], v[176:179], v[42:45]
	v_mfma_f32_16x16x32_bf16 v[30:33], v[152:155], v[184:187], v[30:33]
	v_mfma_f32_16x16x32_bf16 v[26:29], v[160:163], v[184:187], v[26:29]
	v_mfma_f32_16x16x32_bf16 v[14:17], v[152:155], v[192:195], v[14:17]
	v_mfma_f32_16x16x32_bf16 v[10:13], v[160:163], v[192:195], v[10:13]
	s_setprio 0
	s_barrier
	s_add_u32 s16, s16, 0x40080
	s_addc_u32 s17, s17, 0
	s_add_i32 s2, s3, s38
	v_lshl_add_u64 v[144:145], s[16:17], 0, v[132:133]
	s_mov_b32 m0, s2
	s_nop 0
	global_load_lds_dwordx4 v[144:145], off
	v_lshl_add_u64 v[144:145], s[16:17], 0, v[136:137]
	s_add_i32 m0, s2, 0x2000
	s_nop 0
	global_load_lds_dwordx4 v[144:145], off
	s_waitcnt vmcnt(6)
	s_barrier
	s_setprio 1
	v_mfma_f32_16x16x32_bf16 v[54:57], v[216:219], v[164:167], v[54:57]
	v_mfma_f32_16x16x32_bf16 v[50:53], v[224:227], v[164:167], v[50:53]
	v_mfma_f32_16x16x32_bf16 v[38:41], v[216:219], v[172:175], v[38:41]
	v_mfma_f32_16x16x32_bf16 v[34:37], v[224:227], v[172:175], v[34:37]
	v_mfma_f32_16x16x32_bf16 v[22:25], v[216:219], v[180:183], v[22:25]
	v_mfma_f32_16x16x32_bf16 v[18:21], v[224:227], v[180:183], v[18:21]
	v_mfma_f32_16x16x32_bf16 v[6:9], v[216:219], v[188:191], v[6:9]
	v_mfma_f32_16x16x32_bf16 v[2:5], v[224:227], v[188:191], v[2:5]
	v_mfma_f32_16x16x32_bf16 v[54:57], v[220:223], v[168:171], v[54:57]
	v_mfma_f32_16x16x32_bf16 v[50:53], v[228:231], v[168:171], v[50:53]
	v_mfma_f32_16x16x32_bf16 v[38:41], v[220:223], v[176:179], v[38:41]
	v_mfma_f32_16x16x32_bf16 v[34:37], v[228:231], v[176:179], v[34:37]
	v_mfma_f32_16x16x32_bf16 v[22:25], v[220:223], v[184:187], v[22:25]
	v_mfma_f32_16x16x32_bf16 v[18:21], v[228:231], v[184:187], v[18:21]
	v_mfma_f32_16x16x32_bf16 v[6:9], v[220:223], v[192:195], v[6:9]
	v_mfma_f32_16x16x32_bf16 v[2:5], v[228:231], v[192:195], v[2:5]
	s_setprio 0
	s_add_i32 s9, s9, 2
	s_add_u32 s14, s14, 0x100
	s_addc_u32 s15, s15, 0
	s_add_u32 s1, s1, 0x100
	s_addc_u32 s7, s7, 0
	s_cmp_gt_u32 s9, 13
	s_barrier
	s_cbranch_scc0 .LBB0_969
	s_cmpk_gt_u32 s36, 0xff
	s_cbranch_scc1 .Lgx_f_pre
	s_barrier
.Lgx_f_pre:
	s_lshl_b32 s7, s0, 8
	s_add_i32 s7, s7, s43
	s_cmp_gt_i32 s37, 63
	v_mov_b32_e32 v0, 0x3cf
	s_cselect_b64 s[18:19], -1, 0
	s_ashr_i32 s16, s7, 10
	v_bitop3_b32 v148, s7, v0, v139 bitop3:0xc8
	v_lshl_add_u32 v150, v148, 1, s16
	v_ashrrev_i32_e32 v151, 31, v150
	v_readlane_b32 s2, v251, 1
	v_lshlrev_b64 v[150:151], 9, v[150:151]
	v_readlane_b32 s3, v251, 2
	v_lshl_or_b32 v144, s37, 8, v138
	v_cvt_pk_bf16_f32 v126, v126, v127
	v_cvt_pk_bf16_f32 v127, v128, v129
	v_cvt_pk_bf16_f32 v128, v122, v123
	s_mov_b64 s[0:1], -1
	s_and_b64 vcc, exec, s[18:19]
	v_lshl_add_u64 v[122:123], s[2:3], 0, v[150:151]
	v_cvt_pk_bf16_f32 v129, v124, v125
	s_cbranch_vccz .LBB0_972
	v_mov_b32_e32 v145, v1
	s_movk_i32 s0, 0x8000
	v_lshl_add_u64 v[124:125], v[144:145], 1, v[122:123]
	s_mov_b32 s1, -1
	v_lshl_add_u64 v[124:125], v[124:125], 0, s[0:1]
	s_mov_b64 s[0:1], 0

; #define PG8_WAIT_V(n) asm volatile("s_waitcnt vmcnt(" #n ")" ::: "memory")
; #define PG8_BAR __builtin_amdgcn_s_barrier()
; template <class Epi, class Sched>
; __device__ __forceinline__ void gemm_phase(LAS unsigned char* lds, const int K, const int lda, const int ldb, const Sched& S, const Epi& E) {
;     ...
;     PG8_WAIT_V(0);
;     if (wr == 0) PG8_BAR;
;     PG8_BAR;
.LBB0_1034:
	s_waitcnt vmcnt(0)
	s_cmpk_gt_u32 s36, 0xff
	s_movk_i32 s45, 0x3fff
	s_mov_b32 s47, s94
.LBB0_1036:
	s_barrier
